# re-derived MFMA-result wait states (s_nop) after the attention read batching; same schedule otherwise
# speedup vs baseline: 1.0019x; 1.0019x over previous
; template <bool SWA>
; DI void attn_phase(const Ctx& a, LAS unsigned char* lds) {
;     ...
;                 for (int jt = 0; jt < 4; ++jt) {
;                     const int row = 16 * jt + fr; const int sw = (row >> 1) & 7;
;                     const bf16x8 k0 = *(const LAS bf16x8*)(lds + AT_K + buf * 8192 + row * 128 + ((fq ^ sw) << 4));
;                     const bf16x8 k1 = *(const LAS bf16x8*)(lds + AT_K + buf * 8192 + row * 128 + (((4 + fq) ^ sw) << 4));
;                     f32x4 acc = (f32x4){0.f, 0.f, 0.f, 0.f}; acc = MFMA16(k0, qf[0], acc); acc = MFMA16(k1, qf[1], acc); sc[jt] = acc;
;                 }
;                 float sv[16]; bool ok[16];
; #pragma unroll
;                 for (int jt = 0; jt < 4; ++jt)
; #pragma unroll
;                     for (int rr = 0; rr < 4; ++rr) {
;                         bool valid = true;
;                         if (SWA && local) { const int dd = tkey0 + 16 * jt + 4 * fq + rr - (tq0 + fr); valid = (dd <= 128) && (dd >= -128); }
;                         sv[jt * 4 + rr] = valid ? sc[jt][rr] : -1e30f; ok[jt * 4 + rr] = valid;
;                     }
;                 float cmax = sv[0];
; #pragma unroll
;                 for (int e = 1; e < 16; ++e) cmax = fmaxf(cmax, sv[e]);
;                 cmax = fmaxf(cmax, shx(cmax, 16, lane)); cmax = fmaxf(cmax, shx(cmax, 32, lane));
;                 const float m_new = fmaxf(m_run, cmax);
;                 const float alpha = __builtin_amdgcn_exp2f((m_run - m_new) * LOG2E);
;                 float p[16], psum = 0.f;
; #pragma unroll
;                 for (int e = 0; e < 16; ++e) { p[e] = ok[e] ? __builtin_amdgcn_exp2f((sv[e] - m_new) * LOG2E) : 0.f; psum += p[e]; }
;                 l_run = l_run * alpha + psum; m_run = m_new;
;                 u32x4 pw0, pw1; pw0.x = pk2(p[0], p[1]); pw0.y = pk2(p[2], p[3]); pw0.z = pk2(p[4], p[5]); pw0.w = pk2(p[6], p[7]);
;                 pw1.x = pk2(p[8], p[9]); pw1.y = pk2(p[10], p[11]); pw1.z = pk2(p[12], p[13]); pw1.w = pk2(p[14], p[15]);
;                 const bf16x8 pf0 = __builtin_bit_cast(bf16x8, pw0), pf1 = __builtin_bit_cast(bf16x8, pw1);
;                 if (__builtin_amdgcn_ballot_w64(alpha != 1.f) != 0ull) {
; #pragma unroll
;                     for (int dt = 0; dt < 4; ++dt) o[dt] = o[dt] * alpha;
;                 }
;                 const int kc = (fq >> 1), kb8 = (fq & 1) * 8;
; #pragma unroll
.LBB0_78:
	v_add_u32_e32 v79, v65, v66
	v_add_u32_e32 v80, v65, v67
	ds_read_b128 v[0:3], v79
	ds_read_b128 v[4:7], v79 offset:2048
	ds_read_b128 v[8:11], v80
	ds_read_b128 v[20:23], v80 offset:2048
	s_waitcnt lgkmcnt(0)
	v_mfma_f32_16x16x32_bf16 v[0:3], v[0:3], v[12:15], 0
	v_add_u32_e32 v77, v74, v70
	v_add_u32_e32 v78, v74, v71
	v_add_u32_e32 v76, v74, v73
	v_mfma_f32_16x16x32_bf16 v[0:3], v[8:11], v[16:19], v[0:3]
	ds_read_b128 v[8:11], v79 offset:4096
	v_mfma_f32_16x16x32_bf16 v[4:7], v[4:7], v[12:15], 0
	s_nop 5
	v_max_f32_e32 v34, v1, v1
	v_max_f32_e32 v35, v0, v0
	v_mfma_f32_16x16x32_bf16 v[4:7], v[20:23], v[16:19], v[4:7]
	ds_read_b128 v[20:23], v80 offset:4096
	ds_read_b128 v[26:29], v79 offset:6144
	ds_read_b128 v[30:33], v80 offset:6144
	ds_read_b64 v[122:123], v76 offset:24576
	ds_read_b64 v[130:131], v76 offset:26624
	s_waitcnt lgkmcnt(0)
	v_mfma_f32_16x16x32_bf16 v[8:11], v[8:11], v[12:15], 0
	v_mfma_f32_16x16x32_bf16 v[8:11], v[20:23], v[16:19], v[8:11]
	v_max_f32_e32 v20, v35, v34
	v_max3_f32 v20, v20, v2, v3
	v_max3_f32 v34, v20, v4, v5
	v_mfma_f32_16x16x32_bf16 v[20:23], v[26:29], v[12:15], 0
	v_max3_f32 v26, v34, v6, v7
	s_nop 2
	v_max3_f32 v26, v26, v8, v9
	v_max3_f32 v26, v26, v10, v11
	v_mfma_f32_16x16x32_bf16 v[20:23], v[30:33], v[16:19], v[20:23]
	s_nop 6
	s_nop 0
	v_max3_f32 v26, v26, v20, v21
	v_max3_f32 v26, v26, v22, v23
	ds_bpermute_b32 v27, v68, v26
	s_waitcnt lgkmcnt(0)
	v_max_f32_e32 v27, v27, v27
	v_max_f32_e32 v26, v26, v27
	ds_bpermute_b32 v27, v69, v26
	s_waitcnt lgkmcnt(0)
	v_max3_f32 v60, v25, v26, v27
	v_sub_f32_e32 v0, v0, v60
	v_sub_f32_e32 v25, v25, v60
	v_mul_f32_e32 v0, 0x3fb8aa3b, v0
	v_mul_f32_e32 v49, 0x3fb8aa3b, v25
	v_exp_f32_e32 v25, v0
	v_sub_f32_e32 v0, v3, v60
	v_mul_f32_e32 v0, 0x3fb8aa3b, v0
	v_exp_f32_e32 v28, v0
	v_sub_f32_e32 v0, v4, v60
	v_mul_f32_e32 v0, 0x3fb8aa3b, v0
	v_exp_f32_e32 v29, v0
	v_sub_f32_e32 v0, v5, v60
	v_mul_f32_e32 v0, 0x3fb8aa3b, v0
	v_exp_f32_e32 v30, v0
	v_sub_f32_e32 v0, v6, v60
	v_mul_f32_e32 v0, 0x3fb8aa3b, v0
	v_exp_f32_e32 v31, v0
	v_sub_f32_e32 v0, v7, v60
	v_mul_f32_e32 v0, 0x3fb8aa3b, v0
	v_exp_f32_e32 v32, v0
	v_sub_f32_e32 v0, v8, v60
	v_mul_f32_e32 v0, 0x3fb8aa3b, v0
	v_exp_f32_e32 v33, v0
	v_sub_f32_e32 v0, v9, v60
	v_exp_f32_e32 v84, v49
	v_mul_f32_e32 v0, 0x3fb8aa3b, v0
	v_exp_f32_e32 v34, v0
	v_sub_f32_e32 v0, v10, v60
	v_mul_f32_e32 v0, 0x3fb8aa3b, v0
	v_exp_f32_e32 v35, v0
	v_sub_f32_e32 v0, v11, v60
	v_cmp_neq_f32_e32 vcc, 1.0, v84
	v_mul_f32_e32 v0, 0x3fb8aa3b, v0
	s_cmp_lg_u64 vcc, 0
	v_exp_f32_e32 v36, v0
	v_sub_f32_e32 v0, v20, v60
	v_mul_f32_e32 v4, 0, v84
	s_cselect_b64 vcc, -1, 0
	v_mul_f32_e32 v0, 0x3fb8aa3b, v0
	v_cndmask_b32_e32 v90, 0, v4, vcc
	ds_read_b64 v[116:117], v77 offset:24576
	ds_read_b64 v[124:125], v77 offset:26624
	ds_read_b64 v[118:119], v78 offset:24576
	ds_read_b64 v[126:127], v78 offset:26624
	v_exp_f32_e32 v37, v0
	v_sub_f32_e32 v0, v21, v60
	v_mul_f32_e32 v0, 0x3fb8aa3b, v0
	v_sub_f32_e32 v1, v1, v60
	v_sub_f32_e32 v2, v2, v60
	v_exp_f32_e32 v38, v0
	v_sub_f32_e32 v0, v22, v60
	v_add_u32_e32 v49, v74, v72
	v_mul_f32_e32 v1, 0x3fb8aa3b, v1
	v_mul_f32_e32 v2, 0x3fb8aa3b, v2
	v_mul_f32_e32 v0, 0x3fb8aa3b, v0
	ds_read_b64 v[120:121], v49 offset:24576
	ds_read_b64 v[128:129], v49 offset:26624
	v_exp_f32_e32 v26, v1
	v_exp_f32_e32 v27, v2
	v_exp_f32_e32 v39, v0
	v_sub_f32_e32 v0, v23, v60
	s_waitcnt lgkmcnt(0)
	v_mul_f32_e32 v0, 0x3fb8aa3b, v0
	v_exp_f32_e32 v83, v0
	v_cvt_pk_bf16_f32 v0, v25, v26
	v_cvt_pk_bf16_f32 v1, v27, v28
	v_cvt_pk_bf16_f32 v2, v29, v30
	v_cvt_pk_bf16_f32 v3, v31, v32
	v_mov_b32_e32 v91, v90
	v_mov_b32_e32 v92, v90
	v_mov_b32_e32 v93, v90
	s_nop 1
	v_mfma_f32_16x16x32_bf16 v[20:23], v[116:119], v[0:3], v[90:93]
	v_cvt_pk_bf16_f32 v86, v33, v34
	v_cvt_pk_bf16_f32 v87, v35, v36
	v_cvt_pk_bf16_f32 v88, v37, v38
	v_cvt_pk_bf16_f32 v89, v39, v83
	s_nop 1
	v_mfma_f32_16x16x32_bf16 v[20:23], v[120:123], v[86:89], v[20:23]
	ds_read_b64 v[132:133], v77 offset:28672
	ds_read_b64 v[136:137], v77 offset:30720
	ds_read_b64 v[134:135], v78 offset:28672
	ds_read_b64 v[138:139], v78 offset:30720
	s_andn2_b64 vcc, exec, s[30:31]
	s_mov_b64 s[30:31], -1
	v_mfma_f32_16x16x32_bf16 v[4:7], v[124:127], v[0:3], v[90:93]
	v_mfma_f32_16x16x32_bf16 v[8:11], v[128:131], v[86:89], v[4:7]
	ds_read_b64 v[140:141], v49 offset:28672
	ds_read_b64 v[160:161], v49 offset:30720
	ds_read_b64 v[142:143], v76 offset:28672
	ds_read_b64 v[162:163], v76 offset:30720
	s_waitcnt lgkmcnt(0)
	s_nop 2
	v_mfma_f32_16x16x32_bf16 v[4:7], v[132:135], v[0:3], v[90:93]
	v_mfma_f32_16x16x32_bf16 v[0:3], v[136:139], v[0:3], v[90:93]
	v_mfma_f32_16x16x32_bf16 v[4:7], v[140:143], v[86:89], v[4:7]
	v_mfma_f32_16x16x32_bf16 v[0:3], v[160:163], v[86:89], v[0:3]
	s_cbranch_vccnz .LBB0_80
	s_waitcnt vmcnt(0)
	s_mov_b64 s[30:31], 0

; #define LAS __attribute__((address_space(3)))
; template <bool SWA>
; DI void attn_phase(const Ctx& a, LAS unsigned char* lds) {
;     ...
;             if (nck == 2) {
;                 const int tkey0 = rlo + 64 * tl;
;                 f32x4 sc[4];
; #pragma unroll
;                 for (int jt = 0; jt < 4; ++jt) {
;                     const int row = 16 * jt + fr; const int sw = (row >> 1) & 7;
;                     const bf16x8 k0 = *(const LAS bf16x8*)(lds + AT_K + buf * 8192 + row * 128 + ((fq ^ sw) << 4));
;                     const bf16x8 k1 = *(const LAS bf16x8*)(lds + AT_K + buf * 8192 + row * 128 + (((4 + fq) ^ sw) << 4));
;                     f32x4 acc = (f32x4){0.f, 0.f, 0.f, 0.f}; acc = MFMA16(k0, qf[0], acc); acc = MFMA16(k1, qf[1], acc); sc[jt] = acc;
;                 }
;                 float sv[16]; bool ok[16];
; #pragma unroll
;                 for (int jt = 0; jt < 4; ++jt)
; #pragma unroll
;                     for (int rr = 0; rr < 4; ++rr) {
;                         bool valid = true;
;                         if (SWA && local) { const int dd = tkey0 + 16 * jt + 4 * fq + rr - (tq0 + fr); valid = (dd <= 128) && (dd >= -128); }
;                         sv[jt * 4 + rr] = valid ? sc[jt][rr] : -1e30f; ok[jt * 4 + rr] = valid;
;                     }
;                 float cmax = sv[0];
; #pragma unroll
;                 for (int e = 1; e < 16; ++e) cmax = fmaxf(cmax, sv[e]);
;                 cmax = fmaxf(cmax, shx(cmax, 16, lane)); cmax = fmaxf(cmax, shx(cmax, 32, lane));
;                 const float m_new = fmaxf(m_run, cmax);
;                 const float alpha = __builtin_amdgcn_exp2f((m_run - m_new) * LOG2E);
;                 float p[16], psum = 0.f;
; #pragma unroll
;                 for (int e = 0; e < 16; ++e) { p[e] = ok[e] ? __builtin_amdgcn_exp2f((sv[e] - m_new) * LOG2E) : 0.f; psum += p[e]; }
;                 l_run = l_run * alpha + psum; m_run = m_new;
;                 u32x4 pw0, pw1; pw0.x = pk2(p[0], p[1]); pw0.y = pk2(p[2], p[3]); pw0.z = pk2(p[4], p[5]); pw0.w = pk2(p[6], p[7]);
;                 pw1.x = pk2(p[8], p[9]); pw1.y = pk2(p[10], p[11]); pw1.z = pk2(p[12], p[13]); pw1.w = pk2(p[14], p[15]);
;                 const bf16x8 pf0 = __builtin_bit_cast(bf16x8, pw0), pf1 = __builtin_bit_cast(bf16x8, pw1);
;                 if (__builtin_amdgcn_ballot_w64(alpha != 1.f) != 0ull) {
; #pragma unroll
.LBB0_94:
	ds_read_b128 v[164:167], v79 offset:16384
	ds_read_b128 v[168:171], v80 offset:16384
	ds_read_b128 v[172:175], v79 offset:18432
	ds_read_b128 v[176:179], v80 offset:18432
	ds_read_b128 v[180:183], v79 offset:20480
	ds_read_b128 v[184:187], v80 offset:20480
	ds_read_b128 v[192:195], v79 offset:22528
	ds_read_b128 v[196:199], v80 offset:22528
	s_waitcnt lgkmcnt(6)
	v_mfma_f32_16x16x32_bf16 v[24:27], v[164:167], v[12:15], 0
	v_mfma_f32_16x16x32_bf16 v[24:27], v[168:171], v[16:19], v[24:27]
	s_waitcnt lgkmcnt(4)
	v_mfma_f32_16x16x32_bf16 v[28:31], v[172:175], v[12:15], 0
	s_nop 3
	s_nop 1
	v_max_f32_e32 v60, v25, v25
	s_nop 0
	v_max_f32_e32 v81, v24, v24
	v_max_f32_e32 v60, v81, v60
	v_mfma_f32_16x16x32_bf16 v[28:31], v[176:179], v[16:19], v[28:31]
	v_max3_f32 v60, v60, v26, v27
	s_waitcnt lgkmcnt(2)
	v_mfma_f32_16x16x32_bf16 v[32:35], v[180:183], v[12:15], 0
	s_nop 2
	s_nop 1
	v_max3_f32 v60, v60, v28, v29
	s_nop 0
	v_max3_f32 v60, v60, v30, v31
	v_mfma_f32_16x16x32_bf16 v[32:35], v[184:187], v[16:19], v[32:35]
	s_waitcnt lgkmcnt(0)
	v_mfma_f32_16x16x32_bf16 v[36:39], v[192:195], v[12:15], 0
	s_nop 3
	s_nop 1
	v_max3_f32 v60, v60, v32, v33
	s_nop 0
	v_max3_f32 v60, v60, v34, v35
	v_mfma_f32_16x16x32_bf16 v[36:39], v[196:199], v[16:19], v[36:39]
	s_nop 7
	v_max3_f32 v60, v60, v36, v37
	v_max3_f32 v60, v60, v38, v39
	ds_bpermute_b32 v81, v68, v60
	s_waitcnt lgkmcnt(0)
	v_max_f32_e32 v81, v81, v81
	v_max_f32_e32 v60, v60, v81
	ds_bpermute_b32 v81, v69, v60
	s_waitcnt lgkmcnt(0)
	v_max3_f32 v82, v85, v60, v81
	v_sub_f32_e32 v60, v85, v82
	v_mul_f32_e32 v60, 0x3fb8aa3b, v60
	v_exp_f32_e32 v60, v60
	s_nop 0
	v_cmp_neq_f32_e32 vcc, 1.0, v60
	s_cbranch_vccz .LBB0_96
	v_pk_mul_f32 v[22:23], v[22:23], v[60:61] op_sel_hi:[1,0]
	v_pk_mul_f32 v[20:21], v[20:21], v[60:61] op_sel_hi:[1,0]
	v_pk_mul_f32 v[10:11], v[10:11], v[60:61] op_sel_hi:[1,0]
	v_pk_mul_f32 v[8:9], v[8:9], v[60:61] op_sel_hi:[1,0]
	v_pk_mul_f32 v[6:7], v[6:7], v[60:61] op_sel_hi:[1,0]
	v_pk_mul_f32 v[4:5], v[4:5], v[60:61] op_sel_hi:[1,0]
	v_pk_mul_f32 v[2:3], v[2:3], v[60:61] op_sel_hi:[1,0]
	v_pk_mul_f32 v[0:1], v[0:1], v[60:61] op_sel_hi:[1,0]

; #define LAS __attribute__((address_space(3)))
; template <bool SWA>
; DI void attn_phase(const Ctx& a, LAS unsigned char* lds) {
;     ...
;             if (nck == 2) {
;                 const int tkey0 = rlo + 64 * tl;
;                 f32x4 sc[4];
; #pragma unroll
;                 for (int jt = 0; jt < 4; ++jt) {
;                     const int row = 16 * jt + fr; const int sw = (row >> 1) & 7;
;                     const bf16x8 k0 = *(const LAS bf16x8*)(lds + AT_K + buf * 8192 + row * 128 + ((fq ^ sw) << 4));
;                     const bf16x8 k1 = *(const LAS bf16x8*)(lds + AT_K + buf * 8192 + row * 128 + (((4 + fq) ^ sw) << 4));
;                     f32x4 acc = (f32x4){0.f, 0.f, 0.f, 0.f}; acc = MFMA16(k0, qf[0], acc); acc = MFMA16(k1, qf[1], acc); sc[jt] = acc;
;                 }
;                 float sv[16]; bool ok[16];
; #pragma unroll
;                 for (int jt = 0; jt < 4; ++jt)
; #pragma unroll
;                     for (int rr = 0; rr < 4; ++rr) {
;                         bool valid = true;
;                         if (SWA && local) { const int dd = tkey0 + 16 * jt + 4 * fq + rr - (tq0 + fr); valid = (dd <= 128) && (dd >= -128); }
;                         sv[jt * 4 + rr] = valid ? sc[jt][rr] : -1e30f; ok[jt * 4 + rr] = valid;
;                     }
;                 float cmax = sv[0];
; #pragma unroll
;                 for (int e = 1; e < 16; ++e) cmax = fmaxf(cmax, sv[e]);
;                 cmax = fmaxf(cmax, shx(cmax, 16, lane)); cmax = fmaxf(cmax, shx(cmax, 32, lane));
;                 const float m_new = fmaxf(m_run, cmax);
;                 const float alpha = __builtin_amdgcn_exp2f((m_run - m_new) * LOG2E);
;                 float p[16], psum = 0.f;
; #pragma unroll
;                 for (int e = 0; e < 16; ++e) { p[e] = ok[e] ? __builtin_amdgcn_exp2f((sv[e] - m_new) * LOG2E) : 0.f; psum += p[e]; }
;                 l_run = l_run * alpha + psum; m_run = m_new;
;                 u32x4 pw0, pw1; pw0.x = pk2(p[0], p[1]); pw0.y = pk2(p[2], p[3]); pw0.z = pk2(p[4], p[5]); pw0.w = pk2(p[6], p[7]);
;                 pw1.x = pk2(p[8], p[9]); pw1.y = pk2(p[10], p[11]); pw1.z = pk2(p[12], p[13]); pw1.w = pk2(p[14], p[15]);
;                 const bf16x8 pf0 = __builtin_bit_cast(bf16x8, pw0), pf1 = __builtin_bit_cast(bf16x8, pw1);
;                 if (__builtin_amdgcn_ballot_w64(alpha != 1.f) != 0ull) {
; #pragma unroll
.LBB0_103:
	ds_read_b128 v[164:167], v79
	ds_read_b128 v[168:171], v80
	ds_read_b128 v[172:175], v79 offset:2048
	ds_read_b128 v[176:179], v80 offset:2048
	ds_read_b128 v[180:183], v79 offset:4096
	ds_read_b128 v[184:187], v80 offset:4096
	ds_read_b128 v[192:195], v79 offset:6144
	ds_read_b128 v[196:199], v80 offset:6144
	s_waitcnt lgkmcnt(6)
	v_mfma_f32_16x16x32_bf16 v[24:27], v[164:167], v[12:15], 0
	v_mfma_f32_16x16x32_bf16 v[24:27], v[168:171], v[16:19], v[24:27]
	s_waitcnt lgkmcnt(4)
	v_mfma_f32_16x16x32_bf16 v[28:31], v[172:175], v[12:15], 0
	s_nop 3
	s_nop 1
	v_max_f32_e32 v60, v25, v25
	v_mfma_f32_16x16x32_bf16 v[28:31], v[176:179], v[16:19], v[28:31]
	s_waitcnt lgkmcnt(2)
	v_mfma_f32_16x16x32_bf16 v[32:35], v[180:183], v[12:15], 0
	v_mfma_f32_16x16x32_bf16 v[32:35], v[184:187], v[16:19], v[32:35]
	v_max_f32_e32 v79, v24, v24
	v_max_f32_e32 v60, v79, v60
	s_waitcnt lgkmcnt(0)
	v_mfma_f32_16x16x32_bf16 v[36:39], v[192:195], v[12:15], 0
	v_max3_f32 v60, v60, v26, v27
	v_max3_f32 v60, v60, v28, v29
	v_max3_f32 v60, v60, v30, v31
	v_mfma_f32_16x16x32_bf16 v[36:39], v[196:199], v[16:19], v[36:39]
	v_max3_f32 v60, v60, v32, v33
	v_max3_f32 v60, v60, v34, v35
	s_nop 5
	v_max3_f32 v60, v60, v36, v37
	v_max3_f32 v60, v60, v38, v39
	ds_bpermute_b32 v79, v68, v60
	s_waitcnt lgkmcnt(0)
	v_max_f32_e32 v79, v79, v79
	v_max_f32_e32 v60, v60, v79
	ds_bpermute_b32 v79, v69, v60
	s_waitcnt lgkmcnt(0)
	v_max3_f32 v79, v82, v60, v79
	v_sub_f32_e32 v60, v82, v79
	v_mul_f32_e32 v60, 0x3fb8aa3b, v60
	v_exp_f32_e32 v60, v60
	s_nop 0
	v_cmp_neq_f32_e32 vcc, 1.0, v60
	s_cbranch_vccz .LBB0_105
	v_pk_mul_f32 v[22:23], v[22:23], v[60:61] op_sel_hi:[1,0]
	v_pk_mul_f32 v[20:21], v[20:21], v[60:61] op_sel_hi:[1,0]
	v_pk_mul_f32 v[10:11], v[10:11], v[60:61] op_sel_hi:[1,0]
	v_pk_mul_f32 v[8:9], v[8:9], v[60:61] op_sel_hi:[1,0]
	v_pk_mul_f32 v[6:7], v[6:7], v[60:61] op_sel_hi:[1,0]
	v_pk_mul_f32 v[4:5], v[4:5], v[60:61] op_sel_hi:[1,0]
	v_pk_mul_f32 v[2:3], v[2:3], v[60:61] op_sel_hi:[1,0]
	v_pk_mul_f32 v[0:1], v[0:1], v[60:61] op_sel_hi:[1,0]

; #define LAS __attribute__((address_space(3)))
; template <bool SWA>
; DI void attn_phase(const Ctx& a, LAS unsigned char* lds) {
;     ...
;             if (nck == 2) {
;                 const int tkey0 = rlo + 64 * tl;
;                 f32x4 sc[4];
; #pragma unroll
;                 for (int jt = 0; jt < 4; ++jt) {
;                     const int row = 16 * jt + fr; const int sw = (row >> 1) & 7;
;                     const bf16x8 k0 = *(const LAS bf16x8*)(lds + AT_K + buf * 8192 + row * 128 + ((fq ^ sw) << 4));
;                     const bf16x8 k1 = *(const LAS bf16x8*)(lds + AT_K + buf * 8192 + row * 128 + (((4 + fq) ^ sw) << 4));
;                     f32x4 acc = (f32x4){0.f, 0.f, 0.f, 0.f}; acc = MFMA16(k0, qf[0], acc); acc = MFMA16(k1, qf[1], acc); sc[jt] = acc;
;                 }
;                 float sv[16]; bool ok[16];
; #pragma unroll
;                 for (int jt = 0; jt < 4; ++jt)
; #pragma unroll
;                     for (int rr = 0; rr < 4; ++rr) {
;                         bool valid = true;
;                         if (SWA && local) { const int dd = tkey0 + 16 * jt + 4 * fq + rr - (tq0 + fr); valid = (dd <= 128) && (dd >= -128); }
;                         sv[jt * 4 + rr] = valid ? sc[jt][rr] : -1e30f; ok[jt * 4 + rr] = valid;
;                     }
;                 float cmax = sv[0];
; #pragma unroll
;                 for (int e = 1; e < 16; ++e) cmax = fmaxf(cmax, sv[e]);
;                 cmax = fmaxf(cmax, shx(cmax, 16, lane)); cmax = fmaxf(cmax, shx(cmax, 32, lane));
;                 const float m_new = fmaxf(m_run, cmax);
;                 const float alpha = __builtin_amdgcn_exp2f((m_run - m_new) * LOG2E);
;                 float p[16], psum = 0.f;
; #pragma unroll
;                 for (int e = 0; e < 16; ++e) { p[e] = ok[e] ? __builtin_amdgcn_exp2f((sv[e] - m_new) * LOG2E) : 0.f; psum += p[e]; }
;                 l_run = l_run * alpha + psum; m_run = m_new;
;                 u32x4 pw0, pw1; pw0.x = pk2(p[0], p[1]); pw0.y = pk2(p[2], p[3]); pw0.z = pk2(p[4], p[5]); pw0.w = pk2(p[6], p[7]);
;                 pw1.x = pk2(p[8], p[9]); pw1.y = pk2(p[10], p[11]); pw1.z = pk2(p[12], p[13]); pw1.w = pk2(p[14], p[15]);
;                 const bf16x8 pf0 = __builtin_bit_cast(bf16x8, pw0), pf1 = __builtin_bit_cast(bf16x8, pw1);
;                 if (__builtin_amdgcn_ballot_w64(alpha != 1.f) != 0ull) {
; #pragma unroll
.LBB0_160:
	ds_read_b128 v[164:167], v75 offset:16384
	ds_read_b128 v[168:171], v76 offset:16384
	ds_read_b128 v[172:175], v75 offset:18432
	ds_read_b128 v[176:179], v76 offset:18432
	ds_read_b128 v[180:183], v75 offset:20480
	ds_read_b128 v[184:187], v76 offset:20480
	ds_read_b128 v[192:195], v75 offset:22528
	ds_read_b128 v[196:199], v76 offset:22528
	s_waitcnt lgkmcnt(6)
	v_mfma_f32_16x16x32_bf16 v[24:27], v[164:167], v[0:3], 0
	v_mfma_f32_16x16x32_bf16 v[24:27], v[168:171], v[4:7], v[24:27]
	s_waitcnt lgkmcnt(4)
	v_mfma_f32_16x16x32_bf16 v[28:31], v[172:175], v[0:3], 0
	s_nop 3
	s_nop 1
	v_max_f32_e32 v49, v25, v25
	s_nop 0
	v_max_f32_e32 v58, v24, v24
	v_max_f32_e32 v49, v58, v49
	v_mfma_f32_16x16x32_bf16 v[28:31], v[176:179], v[4:7], v[28:31]
	v_max3_f32 v49, v49, v26, v27
	s_waitcnt lgkmcnt(2)
	v_mfma_f32_16x16x32_bf16 v[32:35], v[180:183], v[0:3], 0
	s_nop 2
	s_nop 1
	v_max3_f32 v49, v49, v28, v29
	s_nop 0
	v_max3_f32 v49, v49, v30, v31
	v_mfma_f32_16x16x32_bf16 v[32:35], v[184:187], v[4:7], v[32:35]
	s_waitcnt lgkmcnt(0)
	v_mfma_f32_16x16x32_bf16 v[36:39], v[192:195], v[0:3], 0
	s_nop 3
	s_nop 1
	v_max3_f32 v49, v49, v32, v33
	s_nop 0
	v_max3_f32 v49, v49, v34, v35
	v_mfma_f32_16x16x32_bf16 v[36:39], v[196:199], v[4:7], v[36:39]
	s_nop 7
	v_max3_f32 v49, v49, v36, v37
	v_max3_f32 v49, v49, v38, v39
	ds_bpermute_b32 v58, v69, v49
	s_waitcnt lgkmcnt(0)
	v_max_f32_e32 v58, v58, v58
	v_max_f32_e32 v49, v49, v58
	ds_bpermute_b32 v58, v70, v49
	s_waitcnt lgkmcnt(0)
	v_max3_f32 v85, v87, v49, v58
	v_sub_f32_e32 v49, v87, v85
	v_mul_f32_e32 v49, 0x3fb8aa3b, v49
	v_exp_f32_e32 v58, v49
	s_nop 0
	v_cmp_neq_f32_e32 vcc, 1.0, v58
	s_cbranch_vccz .LBB0_162
	v_pk_mul_f32 v[14:15], v[14:15], v[58:59] op_sel_hi:[1,0]
	v_pk_mul_f32 v[12:13], v[12:13], v[58:59] op_sel_hi:[1,0]
	v_pk_mul_f32 v[18:19], v[18:19], v[58:59] op_sel_hi:[1,0]
	v_pk_mul_f32 v[16:17], v[16:17], v[58:59] op_sel_hi:[1,0]
	v_pk_mul_f32 v[22:23], v[22:23], v[58:59] op_sel_hi:[1,0]
	v_pk_mul_f32 v[20:21], v[20:21], v[58:59] op_sel_hi:[1,0]
	v_pk_mul_f32 v[10:11], v[10:11], v[58:59] op_sel_hi:[1,0]
	v_pk_mul_f32 v[8:9], v[8:9], v[58:59] op_sel_hi:[1,0]

; #define LAS __attribute__((address_space(3)))
; template <bool SWA>
; DI void attn_phase(const Ctx& a, LAS unsigned char* lds) {
;     ...
;             if (nck == 2) {
;                 const int tkey0 = rlo + 64 * tl;
;                 f32x4 sc[4];
; #pragma unroll
;                 for (int jt = 0; jt < 4; ++jt) {
;                     const int row = 16 * jt + fr; const int sw = (row >> 1) & 7;
;                     const bf16x8 k0 = *(const LAS bf16x8*)(lds + AT_K + buf * 8192 + row * 128 + ((fq ^ sw) << 4));
;                     const bf16x8 k1 = *(const LAS bf16x8*)(lds + AT_K + buf * 8192 + row * 128 + (((4 + fq) ^ sw) << 4));
;                     f32x4 acc = (f32x4){0.f, 0.f, 0.f, 0.f}; acc = MFMA16(k0, qf[0], acc); acc = MFMA16(k1, qf[1], acc); sc[jt] = acc;
;                 }
;                 float sv[16]; bool ok[16];
; #pragma unroll
;                 for (int jt = 0; jt < 4; ++jt)
; #pragma unroll
;                     for (int rr = 0; rr < 4; ++rr) {
;                         bool valid = true;
;                         if (SWA && local) { const int dd = tkey0 + 16 * jt + 4 * fq + rr - (tq0 + fr); valid = (dd <= 128) && (dd >= -128); }
;                         sv[jt * 4 + rr] = valid ? sc[jt][rr] : -1e30f; ok[jt * 4 + rr] = valid;
;                     }
;                 float cmax = sv[0];
; #pragma unroll
;                 for (int e = 1; e < 16; ++e) cmax = fmaxf(cmax, sv[e]);
;                 cmax = fmaxf(cmax, shx(cmax, 16, lane)); cmax = fmaxf(cmax, shx(cmax, 32, lane));
;                 const float m_new = fmaxf(m_run, cmax);
;                 const float alpha = __builtin_amdgcn_exp2f((m_run - m_new) * LOG2E);
;                 float p[16], psum = 0.f;
; #pragma unroll
;                 for (int e = 0; e < 16; ++e) { p[e] = ok[e] ? __builtin_amdgcn_exp2f((sv[e] - m_new) * LOG2E) : 0.f; psum += p[e]; }
;                 l_run = l_run * alpha + psum; m_run = m_new;
;                 u32x4 pw0, pw1; pw0.x = pk2(p[0], p[1]); pw0.y = pk2(p[2], p[3]); pw0.z = pk2(p[4], p[5]); pw0.w = pk2(p[6], p[7]);
;                 pw1.x = pk2(p[8], p[9]); pw1.y = pk2(p[10], p[11]); pw1.z = pk2(p[12], p[13]); pw1.w = pk2(p[14], p[15]);
;                 const bf16x8 pf0 = __builtin_bit_cast(bf16x8, pw0), pf1 = __builtin_bit_cast(bf16x8, pw1);
;                 if (__builtin_amdgcn_ballot_w64(alpha != 1.f) != 0ull) {
; #pragma unroll
.LBB0_169:
	ds_read_b128 v[164:167], v75
	ds_read_b128 v[168:171], v76
	ds_read_b128 v[172:175], v75 offset:2048
	ds_read_b128 v[176:179], v76 offset:2048
	ds_read_b128 v[180:183], v75 offset:4096
	ds_read_b128 v[184:187], v76 offset:4096
	ds_read_b128 v[192:195], v75 offset:6144
	ds_read_b128 v[196:199], v76 offset:6144
	s_waitcnt lgkmcnt(6)
	v_mfma_f32_16x16x32_bf16 v[24:27], v[164:167], v[0:3], 0
	v_mfma_f32_16x16x32_bf16 v[24:27], v[168:171], v[4:7], v[24:27]
	s_waitcnt lgkmcnt(4)
	v_mfma_f32_16x16x32_bf16 v[28:31], v[172:175], v[0:3], 0
	s_nop 3
	s_nop 1
	v_max_f32_e32 v49, v25, v25
	s_nop 0
	v_max_f32_e32 v58, v24, v24
	v_max_f32_e32 v49, v58, v49
	v_mfma_f32_16x16x32_bf16 v[28:31], v[176:179], v[4:7], v[28:31]
	v_max3_f32 v49, v49, v26, v27
	s_waitcnt lgkmcnt(2)
	v_mfma_f32_16x16x32_bf16 v[32:35], v[180:183], v[0:3], 0
	s_nop 2
	s_nop 1
	v_max3_f32 v49, v49, v28, v29
	s_nop 0
	v_max3_f32 v49, v49, v30, v31
	v_mfma_f32_16x16x32_bf16 v[32:35], v[184:187], v[4:7], v[32:35]
	s_waitcnt lgkmcnt(0)
	v_mfma_f32_16x16x32_bf16 v[36:39], v[192:195], v[0:3], 0
	s_nop 3
	s_nop 1
	v_max3_f32 v49, v49, v32, v33
	s_nop 0
	v_max3_f32 v49, v49, v34, v35
	v_mfma_f32_16x16x32_bf16 v[36:39], v[196:199], v[4:7], v[36:39]
	s_nop 7
	v_max3_f32 v49, v49, v36, v37
	v_max3_f32 v49, v49, v38, v39
	ds_bpermute_b32 v58, v69, v49
	s_waitcnt lgkmcnt(0)
	v_max_f32_e32 v58, v58, v58
	v_max_f32_e32 v49, v49, v58
	ds_bpermute_b32 v58, v70, v49
	s_waitcnt lgkmcnt(0)
	v_max3_f32 v49, v85, v49, v58
	v_sub_f32_e32 v58, v85, v49
	v_mul_f32_e32 v58, 0x3fb8aa3b, v58
	v_exp_f32_e32 v58, v58
	s_nop 0
	v_cmp_neq_f32_e32 vcc, 1.0, v58
	s_cbranch_vccz .LBB0_171
	v_pk_mul_f32 v[14:15], v[14:15], v[58:59] op_sel_hi:[1,0]
	v_pk_mul_f32 v[12:13], v[12:13], v[58:59] op_sel_hi:[1,0]
	v_pk_mul_f32 v[18:19], v[18:19], v[58:59] op_sel_hi:[1,0]
	v_pk_mul_f32 v[16:17], v[16:17], v[58:59] op_sel_hi:[1,0]
	v_pk_mul_f32 v[22:23], v[22:23], v[58:59] op_sel_hi:[1,0]
	v_pk_mul_f32 v[20:21], v[20:21], v[58:59] op_sel_hi:[1,0]
	v_pk_mul_f32 v[10:11], v[10:11], v[58:59] op_sel_hi:[1,0]
	v_pk_mul_f32 v[8:9], v[8:9], v[58:59] op_sel_hi:[1,0]
